# hand-written k-loops (full-line loads, 3-stage swizzled LDS ring, conflict-free ds_write) in Ph4/Ph5/Ph6
# speedup vs baseline: 1.0639x; 1.0639x over previous
.LBB0_406:
	s_lshl_b32 s6, s5, 5
	s_and_b32 s26, s6, 0xffffff80
	s_lshl_b32 s6, s5, 8
	s_ashr_i32 s27, s26, 31
	s_and_b32 s68, s6, 0x300
	s_lshl_b64 s[8:9], s[26:27], 11
	v_readlane_b32 s7, v252, 50
	v_readlane_b32 s0, v252, 51
	s_nop 1
	s_add_u32 s28, s7, s8
	s_addc_u32 s29, s0, s9
	s_lshl_b32 s7, s68, 11
	s_add_u32 s38, s80, s7
	s_addc_u32 s39, s81, 0
	v_lshrrev_b32_e32 v196, 3, v197
	v_and_b32_e32 v198, 7, v197
	v_lshlrev_b32_e32 v176, 11, v196
	v_lshl_or_b32 v176, v198, 4, v176
	v_add_u32_e32 v177, 0x10000, v176
	v_add_u32_e32 v178, 0x20000, v176
	v_add_u32_e32 v179, 0x30000, v176
	v_add_u32_e32 v180, 0x40000, v176
	v_add_u32_e32 v181, 0x50000, v176
	v_add_u32_e32 v182, 0x60000, v176
	v_add_u32_e32 v184, 0x70000, v176
	global_load_dwordx4 v[128:131], v176, s[28:29]
	global_load_dwordx4 v[132:135], v177, s[28:29]
	global_load_dwordx4 v[136:139], v178, s[28:29]
	global_load_dwordx4 v[140:143], v179, s[28:29]
	global_load_dwordx4 v[144:147], v176, s[38:39]
	global_load_dwordx4 v[148:151], v177, s[38:39]
	global_load_dwordx4 v[152:155], v178, s[38:39]
	global_load_dwordx4 v[156:159], v179, s[38:39]
	global_load_dwordx4 v[160:163], v180, s[38:39]
	global_load_dwordx4 v[164:167], v181, s[38:39]
	global_load_dwordx4 v[168:171], v182, s[38:39]
	global_load_dwordx4 v[172:175], v184, s[38:39]
	s_add_u32 s28, s28, 0x80
	s_addc_u32 s29, s29, 0
	s_add_u32 s38, s38, 0x80
	s_addc_u32 s39, s39, 0
	v_bfe_u32 v217, v197, 5, 2
	v_and_b32_e32 v218, 3, v198
	v_xor_b32_e32 v218, v218, v217
	v_lshlrev_b32_e32 v218, 4, v218
	v_lshl_or_b32 v185, v196, 6, v218
	v_lshrrev_b32_e32 v217, 2, v198
	v_lshlrev_b32_e32 v218, 6, v217
	v_xor_b32_e32 v185, v185, v218
	v_mul_u32_u24_e32 v217, 0x6000, v217
	v_add_u32_e32 v185, v185, v217
	v_and_b32_e32 v196, 31, v197
	v_bfe_u32 v198, v197, 5, 1
	v_bfe_u32 v217, v197, 2, 2
	v_xor_b32_e32 v218, v198, v217
	v_xor_b32_e32 v221, 2, v218
	v_lshrrev_b32_e32 v198, 7, v197
	v_lshl_or_b32 v198, v198, 6, v196
	v_lshlrev_b32_e32 v198, 6, v198
	v_lshl_or_b32 v186, v218, 4, v198
	v_lshl_or_b32 v187, v221, 4, v198
	v_bfe_u32 v198, v197, 6, 1
	v_mul_u32_u24_e32 v198, 128, v198
	v_add_u32_e32 v198, v198, v196
	v_lshlrev_b32_e32 v198, 6, v198
	v_add_u32_e32 v198, 0x2000, v198
	v_lshl_or_b32 v188, v218, 4, v198
	v_lshl_or_b32 v189, v221, 4, v198
	v_mov_b32_e32 v0, 0
	v_mov_b32_e32 v1, 0
	v_mov_b32_e32 v2, 0
	v_mov_b32_e32 v3, 0
	v_mov_b32_e32 v4, 0
	v_mov_b32_e32 v5, 0
	v_mov_b32_e32 v6, 0
	v_mov_b32_e32 v7, 0
	v_mov_b32_e32 v8, 0
	v_mov_b32_e32 v9, 0
	v_mov_b32_e32 v10, 0
	v_mov_b32_e32 v11, 0
	v_mov_b32_e32 v12, 0
	v_mov_b32_e32 v13, 0
	v_mov_b32_e32 v14, 0
	v_mov_b32_e32 v15, 0
	v_mov_b32_e32 v16, 0
	v_mov_b32_e32 v17, 0
	v_mov_b32_e32 v18, 0
	v_mov_b32_e32 v19, 0
	v_mov_b32_e32 v20, 0
	v_mov_b32_e32 v21, 0
	v_mov_b32_e32 v22, 0
	v_mov_b32_e32 v23, 0
	v_mov_b32_e32 v24, 0
	v_mov_b32_e32 v25, 0
	v_mov_b32_e32 v26, 0
	v_mov_b32_e32 v27, 0
	v_mov_b32_e32 v28, 0
	v_mov_b32_e32 v29, 0
	v_mov_b32_e32 v30, 0
	v_mov_b32_e32 v31, 0
	v_mov_b32_e32 v32, 0
	v_mov_b32_e32 v33, 0
	v_mov_b32_e32 v34, 0
	v_mov_b32_e32 v35, 0
	v_mov_b32_e32 v36, 0
	v_mov_b32_e32 v37, 0
	v_mov_b32_e32 v38, 0
	v_mov_b32_e32 v39, 0
	v_mov_b32_e32 v40, 0
	v_mov_b32_e32 v41, 0
	v_mov_b32_e32 v42, 0
	v_mov_b32_e32 v43, 0
	v_mov_b32_e32 v44, 0
	v_mov_b32_e32 v45, 0
	v_mov_b32_e32 v46, 0
	v_mov_b32_e32 v47, 0
	v_mov_b32_e32 v48, 0
	v_mov_b32_e32 v49, 0
	v_mov_b32_e32 v50, 0
	v_mov_b32_e32 v51, 0
	v_mov_b32_e32 v52, 0
	v_mov_b32_e32 v53, 0
	v_mov_b32_e32 v54, 0
	v_mov_b32_e32 v55, 0
	v_mov_b32_e32 v56, 0
	v_mov_b32_e32 v57, 0
	v_mov_b32_e32 v58, 0
	v_mov_b32_e32 v59, 0
	v_mov_b32_e32 v60, 0
	v_mov_b32_e32 v61, 0
	v_mov_b32_e32 v62, 0
	v_mov_b32_e32 v63, 0
	v_mov_b32_e32 v64, 0
	v_mov_b32_e32 v65, 0
	v_mov_b32_e32 v66, 0
	v_mov_b32_e32 v67, 0
	v_mov_b32_e32 v68, 0
	v_mov_b32_e32 v69, 0
	v_mov_b32_e32 v70, 0
	v_mov_b32_e32 v71, 0
	v_mov_b32_e32 v72, 0
	v_mov_b32_e32 v73, 0
	v_mov_b32_e32 v74, 0
	v_mov_b32_e32 v75, 0
	v_mov_b32_e32 v76, 0
	v_mov_b32_e32 v77, 0
	v_mov_b32_e32 v78, 0
	v_mov_b32_e32 v79, 0
	v_mov_b32_e32 v80, 0
	v_mov_b32_e32 v81, 0
	v_mov_b32_e32 v82, 0
	v_mov_b32_e32 v83, 0
	v_mov_b32_e32 v84, 0
	v_mov_b32_e32 v85, 0
	v_mov_b32_e32 v86, 0
	v_mov_b32_e32 v87, 0
	v_mov_b32_e32 v88, 0
	v_mov_b32_e32 v89, 0
	v_mov_b32_e32 v90, 0
	v_mov_b32_e32 v91, 0
	v_mov_b32_e32 v92, 0
	v_mov_b32_e32 v93, 0
	v_mov_b32_e32 v94, 0
	v_mov_b32_e32 v95, 0
	v_mov_b32_e32 v96, 0
	v_mov_b32_e32 v97, 0
	v_mov_b32_e32 v98, 0
	v_mov_b32_e32 v99, 0
	v_mov_b32_e32 v100, 0
	v_mov_b32_e32 v101, 0
	v_mov_b32_e32 v102, 0
	v_mov_b32_e32 v103, 0
	v_mov_b32_e32 v104, 0
	v_mov_b32_e32 v105, 0
	v_mov_b32_e32 v106, 0
	v_mov_b32_e32 v107, 0
	v_mov_b32_e32 v108, 0
	v_mov_b32_e32 v109, 0
	v_mov_b32_e32 v110, 0
	v_mov_b32_e32 v111, 0
	v_mov_b32_e32 v112, 0
	v_mov_b32_e32 v113, 0
	v_mov_b32_e32 v114, 0
	v_mov_b32_e32 v115, 0
	v_mov_b32_e32 v116, 0
	v_mov_b32_e32 v117, 0
	v_mov_b32_e32 v118, 0
	v_mov_b32_e32 v119, 0
	v_mov_b32_e32 v120, 0
	v_mov_b32_e32 v121, 0
	v_mov_b32_e32 v122, 0
	v_mov_b32_e32 v123, 0
	v_mov_b32_e32 v124, 0
	v_mov_b32_e32 v125, 0
	v_mov_b32_e32 v126, 0
	v_mov_b32_e32 v127, 0
	s_mov_b32 s40, 0
	s_mov_b32 s41, 0x6000
	s_mov_b32 s7, 0
	s_waitcnt vmcnt(11)
	ds_write_b128 v185, v[128:131]
	s_waitcnt vmcnt(10)
	ds_write_b128 v185, v[132:135] offset:2048
	s_waitcnt vmcnt(9)
	ds_write_b128 v185, v[136:139] offset:4096
	s_waitcnt vmcnt(8)
	ds_write_b128 v185, v[140:143] offset:6144
	s_waitcnt vmcnt(7)
	ds_write_b128 v185, v[144:147] offset:8192
	s_waitcnt vmcnt(6)
	ds_write_b128 v185, v[148:151] offset:10240
	s_waitcnt vmcnt(5)
	ds_write_b128 v185, v[152:155] offset:12288
	s_waitcnt vmcnt(4)
	ds_write_b128 v185, v[156:159] offset:14336
	s_waitcnt vmcnt(3)
	ds_write_b128 v185, v[160:163] offset:16384
	s_waitcnt vmcnt(2)
	ds_write_b128 v185, v[164:167] offset:18432
	s_waitcnt vmcnt(1)
	ds_write_b128 v185, v[168:171] offset:20480
	s_waitcnt vmcnt(0)
	ds_write_b128 v185, v[172:175] offset:22528
	v_subrev_u32_e32 v196, 0x6000, v185
	v_add_u32_e32 v198, 0xc000, v185
	v_min_u32_e32 v185, v196, v198
	s_waitcnt lgkmcnt(0)
	s_barrier
.Lg4_loop:
	v_add_u32_e32 v190, s40, v186
	v_add_u32_e32 v191, s40, v187
	v_add_u32_e32 v250, s40, v188
	v_add_u32_e32 v251, s40, v189
	ds_read_b128 v[200:203], v190
	ds_read_b128 v[204:207], v190 offset:2048
	ds_read_b128 v[222:225], v250
	ds_read_b128 v[226:229], v250 offset:2048
	ds_read_b128 v[230:233], v250 offset:4096
	ds_read_b128 v[234:237], v250 offset:6144
	ds_read_b128 v[208:211], v191
	ds_read_b128 v[212:215], v191 offset:2048
	ds_read_b128 v[238:241], v251
	ds_read_b128 v[242:245], v251 offset:2048
	ds_read_b128 v[246:249], v251 offset:4096
	ds_read_b128 v[192:195], v251 offset:6144
	s_setprio 1
	s_waitcnt lgkmcnt(9)
	v_mfma_f32_32x32x16_bf16 v[112:127], v[200:203], v[222:225], v[112:127]
	global_load_dwordx4 v[128:131], v176, s[28:29]
	v_mfma_f32_32x32x16_bf16 v[48:63], v[204:207], v[222:225], v[48:63]
	global_load_dwordx4 v[132:135], v177, s[28:29]
	s_waitcnt lgkmcnt(8)
	v_mfma_f32_32x32x16_bf16 v[96:111], v[200:203], v[226:229], v[96:111]
	global_load_dwordx4 v[136:139], v178, s[28:29]
	v_mfma_f32_32x32x16_bf16 v[32:47], v[204:207], v[226:229], v[32:47]
	global_load_dwordx4 v[140:143], v179, s[28:29]
	s_waitcnt lgkmcnt(7)
	v_mfma_f32_32x32x16_bf16 v[80:95], v[200:203], v[230:233], v[80:95]
	global_load_dwordx4 v[144:147], v176, s[38:39]
	v_mfma_f32_32x32x16_bf16 v[16:31], v[204:207], v[230:233], v[16:31]
	global_load_dwordx4 v[148:151], v177, s[38:39]
	s_waitcnt lgkmcnt(6)
	v_mfma_f32_32x32x16_bf16 v[64:79], v[200:203], v[234:237], v[64:79]
	global_load_dwordx4 v[152:155], v178, s[38:39]
	v_mfma_f32_32x32x16_bf16 v[0:15], v[204:207], v[234:237], v[0:15]
	global_load_dwordx4 v[156:159], v179, s[38:39]
	s_waitcnt lgkmcnt(3)
	v_mfma_f32_32x32x16_bf16 v[112:127], v[208:211], v[238:241], v[112:127]
	global_load_dwordx4 v[160:163], v180, s[38:39]
	v_mfma_f32_32x32x16_bf16 v[48:63], v[212:215], v[238:241], v[48:63]
	global_load_dwordx4 v[164:167], v181, s[38:39]
	s_waitcnt lgkmcnt(2)
	v_mfma_f32_32x32x16_bf16 v[96:111], v[208:211], v[242:245], v[96:111]
	global_load_dwordx4 v[168:171], v182, s[38:39]
	v_mfma_f32_32x32x16_bf16 v[32:47], v[212:215], v[242:245], v[32:47]
	global_load_dwordx4 v[172:175], v184, s[38:39]
	s_waitcnt lgkmcnt(1)
	v_mfma_f32_32x32x16_bf16 v[80:95], v[208:211], v[246:249], v[80:95]
	v_mfma_f32_32x32x16_bf16 v[16:31], v[212:215], v[246:249], v[16:31]
	s_waitcnt lgkmcnt(0)
	v_mfma_f32_32x32x16_bf16 v[64:79], v[208:211], v[192:195], v[64:79]
	v_mfma_f32_32x32x16_bf16 v[0:15], v[212:215], v[192:195], v[0:15]
	s_setprio 0
	s_barrier
	v_xad_u32 v190, v186, 64, s41
	v_xad_u32 v191, v187, 64, s41
	v_xad_u32 v250, v188, 64, s41
	v_xad_u32 v251, v189, 64, s41
	ds_read_b128 v[200:203], v190
	ds_read_b128 v[204:207], v190 offset:2048
	ds_read_b128 v[222:225], v250
	ds_read_b128 v[226:229], v250 offset:2048
	ds_read_b128 v[230:233], v250 offset:4096
	ds_read_b128 v[234:237], v250 offset:6144
	ds_read_b128 v[208:211], v191
	ds_read_b128 v[212:215], v191 offset:2048
	ds_read_b128 v[238:241], v251
	ds_read_b128 v[242:245], v251 offset:2048
	ds_read_b128 v[246:249], v251 offset:4096
	ds_read_b128 v[192:195], v251 offset:6144
	s_setprio 1
	s_waitcnt lgkmcnt(9)
	v_mfma_f32_32x32x16_bf16 v[112:127], v[200:203], v[222:225], v[112:127]
	v_mfma_f32_32x32x16_bf16 v[48:63], v[204:207], v[222:225], v[48:63]
	s_waitcnt lgkmcnt(8)
	v_mfma_f32_32x32x16_bf16 v[96:111], v[200:203], v[226:229], v[96:111]
	s_waitcnt vmcnt(11)
	ds_write_b128 v185, v[128:131]
	v_mfma_f32_32x32x16_bf16 v[32:47], v[204:207], v[226:229], v[32:47]
	s_waitcnt vmcnt(10)
	ds_write_b128 v185, v[132:135] offset:2048
	s_waitcnt lgkmcnt(9)
	v_mfma_f32_32x32x16_bf16 v[80:95], v[200:203], v[230:233], v[80:95]
	s_waitcnt vmcnt(9)
	ds_write_b128 v185, v[136:139] offset:4096
	v_mfma_f32_32x32x16_bf16 v[16:31], v[204:207], v[230:233], v[16:31]
	s_waitcnt vmcnt(8)
	ds_write_b128 v185, v[140:143] offset:6144
	s_waitcnt lgkmcnt(10)
	v_mfma_f32_32x32x16_bf16 v[64:79], v[200:203], v[234:237], v[64:79]
	s_waitcnt vmcnt(7)
	ds_write_b128 v185, v[144:147] offset:8192
	v_mfma_f32_32x32x16_bf16 v[0:15], v[204:207], v[234:237], v[0:15]
	s_waitcnt vmcnt(6)
	ds_write_b128 v185, v[148:151] offset:10240
	s_waitcnt lgkmcnt(9)
	v_mfma_f32_32x32x16_bf16 v[112:127], v[208:211], v[238:241], v[112:127]
	s_waitcnt vmcnt(5)
	ds_write_b128 v185, v[152:155] offset:12288
	v_mfma_f32_32x32x16_bf16 v[48:63], v[212:215], v[238:241], v[48:63]
	s_waitcnt vmcnt(4)
	ds_write_b128 v185, v[156:159] offset:14336
	s_waitcnt lgkmcnt(10)
	v_mfma_f32_32x32x16_bf16 v[96:111], v[208:211], v[242:245], v[96:111]
	s_waitcnt vmcnt(3)
	ds_write_b128 v185, v[160:163] offset:16384
	v_mfma_f32_32x32x16_bf16 v[32:47], v[212:215], v[242:245], v[32:47]
	s_waitcnt vmcnt(2)
	ds_write_b128 v185, v[164:167] offset:18432
	s_waitcnt lgkmcnt(11)
	v_mfma_f32_32x32x16_bf16 v[80:95], v[208:211], v[246:249], v[80:95]
	s_waitcnt vmcnt(1)
	ds_write_b128 v185, v[168:171] offset:20480
	v_mfma_f32_32x32x16_bf16 v[16:31], v[212:215], v[246:249], v[16:31]
	s_waitcnt vmcnt(0)
	ds_write_b128 v185, v[172:175] offset:22528
	s_waitcnt lgkmcnt(12)
	v_mfma_f32_32x32x16_bf16 v[64:79], v[208:211], v[192:195], v[64:79]
	v_mfma_f32_32x32x16_bf16 v[0:15], v[212:215], v[192:195], v[0:15]
	s_setprio 0
	s_add_u32 s28, s28, 0x80
	s_addc_u32 s29, s29, 0
	s_add_u32 s38, s38, 0x80
	s_addc_u32 s39, s39, 0
	s_sub_i32 s40, s40, 0x6000
	s_cmp_lt_i32 s40, 0
	s_cselect_b32 s42, 0x12000, 0
	s_add_i32 s40, s40, s42
	s_sub_i32 s41, s41, 0x6000
	s_cmp_lt_i32 s41, 0
	s_cselect_b32 s42, 0x12000, 0
	s_add_i32 s41, s41, s42
	v_subrev_u32_e32 v196, 0x6000, v185
	v_add_u32_e32 v198, 0xc000, v185
	v_min_u32_e32 v185, v196, v198
	s_add_i32 s7, s7, 1
	s_cmp_lt_u32 s7, 15
	s_waitcnt lgkmcnt(0)
	s_barrier
	s_cbranch_scc1 .Lg4_loop
	v_add_u32_e32 v190, s40, v186
	v_add_u32_e32 v191, s40, v187
	v_add_u32_e32 v250, s40, v188
	v_add_u32_e32 v251, s40, v189
	ds_read_b128 v[200:203], v190
	ds_read_b128 v[204:207], v190 offset:2048
	ds_read_b128 v[222:225], v250
	ds_read_b128 v[226:229], v250 offset:2048
	ds_read_b128 v[230:233], v250 offset:4096
	ds_read_b128 v[234:237], v250 offset:6144
	ds_read_b128 v[208:211], v191
	ds_read_b128 v[212:215], v191 offset:2048
	ds_read_b128 v[238:241], v251
	ds_read_b128 v[242:245], v251 offset:2048
	ds_read_b128 v[246:249], v251 offset:4096
	ds_read_b128 v[192:195], v251 offset:6144
	s_setprio 1
	s_waitcnt lgkmcnt(9)
	v_mfma_f32_32x32x16_bf16 v[112:127], v[200:203], v[222:225], v[112:127]
	v_mfma_f32_32x32x16_bf16 v[48:63], v[204:207], v[222:225], v[48:63]
	s_waitcnt lgkmcnt(8)
	v_mfma_f32_32x32x16_bf16 v[96:111], v[200:203], v[226:229], v[96:111]
	v_mfma_f32_32x32x16_bf16 v[32:47], v[204:207], v[226:229], v[32:47]
	s_waitcnt lgkmcnt(7)
	v_mfma_f32_32x32x16_bf16 v[80:95], v[200:203], v[230:233], v[80:95]
	v_mfma_f32_32x32x16_bf16 v[16:31], v[204:207], v[230:233], v[16:31]
	s_waitcnt lgkmcnt(6)
	v_mfma_f32_32x32x16_bf16 v[64:79], v[200:203], v[234:237], v[64:79]
	v_mfma_f32_32x32x16_bf16 v[0:15], v[204:207], v[234:237], v[0:15]
	s_waitcnt lgkmcnt(3)
	v_mfma_f32_32x32x16_bf16 v[112:127], v[208:211], v[238:241], v[112:127]
	v_mfma_f32_32x32x16_bf16 v[48:63], v[212:215], v[238:241], v[48:63]
	s_waitcnt lgkmcnt(2)
	v_mfma_f32_32x32x16_bf16 v[96:111], v[208:211], v[242:245], v[96:111]
	v_mfma_f32_32x32x16_bf16 v[32:47], v[212:215], v[242:245], v[32:47]
	s_waitcnt lgkmcnt(1)
	v_mfma_f32_32x32x16_bf16 v[80:95], v[208:211], v[246:249], v[80:95]
	v_mfma_f32_32x32x16_bf16 v[16:31], v[212:215], v[246:249], v[16:31]
	s_waitcnt lgkmcnt(0)
	v_mfma_f32_32x32x16_bf16 v[64:79], v[208:211], v[192:195], v[64:79]
	v_mfma_f32_32x32x16_bf16 v[0:15], v[212:215], v[192:195], v[0:15]
	s_setprio 0
	v_xad_u32 v190, v186, 64, s41
	v_xad_u32 v191, v187, 64, s41
	v_xad_u32 v250, v188, 64, s41
	v_xad_u32 v251, v189, 64, s41
	ds_read_b128 v[200:203], v190
	ds_read_b128 v[204:207], v190 offset:2048
	ds_read_b128 v[222:225], v250
	ds_read_b128 v[226:229], v250 offset:2048
	ds_read_b128 v[230:233], v250 offset:4096
	ds_read_b128 v[234:237], v250 offset:6144
	ds_read_b128 v[208:211], v191
	ds_read_b128 v[212:215], v191 offset:2048
	ds_read_b128 v[238:241], v251
	ds_read_b128 v[242:245], v251 offset:2048
	ds_read_b128 v[246:249], v251 offset:4096
	ds_read_b128 v[192:195], v251 offset:6144
	s_setprio 1
	s_waitcnt lgkmcnt(9)
	v_mfma_f32_32x32x16_bf16 v[112:127], v[200:203], v[222:225], v[112:127]
	v_mfma_f32_32x32x16_bf16 v[48:63], v[204:207], v[222:225], v[48:63]
	s_waitcnt lgkmcnt(8)
	v_mfma_f32_32x32x16_bf16 v[96:111], v[200:203], v[226:229], v[96:111]
	v_mfma_f32_32x32x16_bf16 v[32:47], v[204:207], v[226:229], v[32:47]
	s_waitcnt lgkmcnt(7)
	v_mfma_f32_32x32x16_bf16 v[80:95], v[200:203], v[230:233], v[80:95]
	v_mfma_f32_32x32x16_bf16 v[16:31], v[204:207], v[230:233], v[16:31]
	s_waitcnt lgkmcnt(6)
	v_mfma_f32_32x32x16_bf16 v[64:79], v[200:203], v[234:237], v[64:79]
	v_mfma_f32_32x32x16_bf16 v[0:15], v[204:207], v[234:237], v[0:15]
	s_waitcnt lgkmcnt(3)
	v_mfma_f32_32x32x16_bf16 v[112:127], v[208:211], v[238:241], v[112:127]
	v_mfma_f32_32x32x16_bf16 v[48:63], v[212:215], v[238:241], v[48:63]
	s_waitcnt lgkmcnt(2)
	v_mfma_f32_32x32x16_bf16 v[96:111], v[208:211], v[242:245], v[96:111]
	v_mfma_f32_32x32x16_bf16 v[32:47], v[212:215], v[242:245], v[32:47]
	s_waitcnt lgkmcnt(1)
	v_mfma_f32_32x32x16_bf16 v[80:95], v[208:211], v[246:249], v[80:95]
	v_mfma_f32_32x32x16_bf16 v[16:31], v[212:215], v[246:249], v[16:31]
	s_waitcnt lgkmcnt(0)
	v_mfma_f32_32x32x16_bf16 v[64:79], v[208:211], v[192:195], v[64:79]
	v_mfma_f32_32x32x16_bf16 v[0:15], v[212:215], v[192:195], v[0:15]
	s_setprio 0
	s_nop 7
	s_nop 7

.LBB0_488:
	s_or_b64 exec, exec, s[26:27]
	s_lshl_b32 s6, s7, 8
	s_lshl_b64 s[40:41], s[0:1], 11
	s_add_u32 s26, s66, s40
	s_addc_u32 s27, s67, s41
	s_lshl_b32 s7, s7, 19
	s_add_u32 s28, s2, s7
	s_addc_u32 s29, s3, 0
	v_lshrrev_b32_e32 v196, 3, v197
	v_and_b32_e32 v198, 7, v197
	v_lshlrev_b32_e32 v178, 11, v196
	v_lshl_or_b32 v178, v198, 4, v178
	v_add_u32_e32 v179, 0x10000, v178
	v_add_u32_e32 v180, 0x20000, v178
	v_add_u32_e32 v181, 0x30000, v178
	v_add_u32_e32 v182, 0x40000, v178
	v_add_u32_e32 v183, 0x50000, v178
	v_add_u32_e32 v184, 0x60000, v178
	v_add_u32_e32 v185, 0x70000, v178
	global_load_dwordx4 v[128:131], v178, s[26:27]
	global_load_dwordx4 v[132:135], v179, s[26:27]
	global_load_dwordx4 v[136:139], v180, s[26:27]
	global_load_dwordx4 v[140:143], v181, s[26:27]
	global_load_dwordx4 v[144:147], v178, s[28:29]
	global_load_dwordx4 v[148:151], v179, s[28:29]
	global_load_dwordx4 v[152:155], v180, s[28:29]
	global_load_dwordx4 v[156:159], v181, s[28:29]
	global_load_dwordx4 v[160:163], v182, s[28:29]
	global_load_dwordx4 v[164:167], v183, s[28:29]
	global_load_dwordx4 v[168:171], v184, s[28:29]
	global_load_dwordx4 v[172:175], v185, s[28:29]
	s_add_u32 s26, s26, 0x80
	s_addc_u32 s27, s27, 0
	s_add_u32 s28, s28, 0x80
	s_addc_u32 s29, s29, 0
	v_bfe_u32 v217, v197, 5, 2
	v_and_b32_e32 v218, 3, v198
	v_xor_b32_e32 v218, v218, v217
	v_lshlrev_b32_e32 v218, 4, v218
	v_lshl_or_b32 v177, v196, 6, v218
	v_lshrrev_b32_e32 v217, 2, v198
	v_lshlrev_b32_e32 v218, 6, v217
	v_xor_b32_e32 v177, v177, v218
	v_mul_u32_u24_e32 v217, 0x6000, v217
	v_add_u32_e32 v177, v177, v217
	v_and_b32_e32 v196, 31, v197
	v_bfe_u32 v198, v197, 5, 1
	v_bfe_u32 v217, v197, 2, 2
	v_xor_b32_e32 v218, v198, v217
	v_xor_b32_e32 v221, 2, v218
	v_lshrrev_b32_e32 v198, 7, v197
	v_lshl_or_b32 v198, v198, 6, v196
	v_lshlrev_b32_e32 v198, 6, v198
	v_lshl_or_b32 v186, v218, 4, v198
	v_lshl_or_b32 v187, v221, 4, v198
	v_bfe_u32 v198, v197, 6, 1
	v_mul_u32_u24_e32 v198, 128, v198
	v_add_u32_e32 v198, v198, v196
	v_lshlrev_b32_e32 v198, 6, v198
	v_add_u32_e32 v198, 0x2000, v198
	v_lshl_or_b32 v188, v218, 4, v198
	v_lshl_or_b32 v189, v221, 4, v198
	v_mov_b32_e32 v0, 0
	v_mov_b32_e32 v1, 0
	v_mov_b32_e32 v2, 0
	v_mov_b32_e32 v3, 0
	v_mov_b32_e32 v4, 0
	v_mov_b32_e32 v5, 0
	v_mov_b32_e32 v6, 0
	v_mov_b32_e32 v7, 0
	v_mov_b32_e32 v8, 0
	v_mov_b32_e32 v9, 0
	v_mov_b32_e32 v10, 0
	v_mov_b32_e32 v11, 0
	v_mov_b32_e32 v12, 0
	v_mov_b32_e32 v13, 0
	v_mov_b32_e32 v14, 0
	v_mov_b32_e32 v15, 0
	v_mov_b32_e32 v16, 0
	v_mov_b32_e32 v17, 0
	v_mov_b32_e32 v18, 0
	v_mov_b32_e32 v19, 0
	v_mov_b32_e32 v20, 0
	v_mov_b32_e32 v21, 0
	v_mov_b32_e32 v22, 0
	v_mov_b32_e32 v23, 0
	v_mov_b32_e32 v24, 0
	v_mov_b32_e32 v25, 0
	v_mov_b32_e32 v26, 0
	v_mov_b32_e32 v27, 0
	v_mov_b32_e32 v28, 0
	v_mov_b32_e32 v29, 0
	v_mov_b32_e32 v30, 0
	v_mov_b32_e32 v31, 0
	v_mov_b32_e32 v32, 0
	v_mov_b32_e32 v33, 0
	v_mov_b32_e32 v34, 0
	v_mov_b32_e32 v35, 0
	v_mov_b32_e32 v36, 0
	v_mov_b32_e32 v37, 0
	v_mov_b32_e32 v38, 0
	v_mov_b32_e32 v39, 0
	v_mov_b32_e32 v40, 0
	v_mov_b32_e32 v41, 0
	v_mov_b32_e32 v42, 0
	v_mov_b32_e32 v43, 0
	v_mov_b32_e32 v44, 0
	v_mov_b32_e32 v45, 0
	v_mov_b32_e32 v46, 0
	v_mov_b32_e32 v47, 0
	v_mov_b32_e32 v48, 0
	v_mov_b32_e32 v49, 0
	v_mov_b32_e32 v50, 0
	v_mov_b32_e32 v51, 0
	v_mov_b32_e32 v52, 0
	v_mov_b32_e32 v53, 0
	v_mov_b32_e32 v54, 0
	v_mov_b32_e32 v55, 0
	v_mov_b32_e32 v56, 0
	v_mov_b32_e32 v57, 0
	v_mov_b32_e32 v58, 0
	v_mov_b32_e32 v59, 0
	v_mov_b32_e32 v60, 0
	v_mov_b32_e32 v61, 0
	v_mov_b32_e32 v62, 0
	v_mov_b32_e32 v63, 0
	v_mov_b32_e32 v64, 0
	v_mov_b32_e32 v65, 0
	v_mov_b32_e32 v66, 0
	v_mov_b32_e32 v67, 0
	v_mov_b32_e32 v68, 0
	v_mov_b32_e32 v69, 0
	v_mov_b32_e32 v70, 0
	v_mov_b32_e32 v71, 0
	v_mov_b32_e32 v72, 0
	v_mov_b32_e32 v73, 0
	v_mov_b32_e32 v74, 0
	v_mov_b32_e32 v75, 0
	v_mov_b32_e32 v76, 0
	v_mov_b32_e32 v77, 0
	v_mov_b32_e32 v78, 0
	v_mov_b32_e32 v79, 0
	v_mov_b32_e32 v80, 0
	v_mov_b32_e32 v81, 0
	v_mov_b32_e32 v82, 0
	v_mov_b32_e32 v83, 0
	v_mov_b32_e32 v84, 0
	v_mov_b32_e32 v85, 0
	v_mov_b32_e32 v86, 0
	v_mov_b32_e32 v87, 0
	v_mov_b32_e32 v88, 0
	v_mov_b32_e32 v89, 0
	v_mov_b32_e32 v90, 0
	v_mov_b32_e32 v91, 0
	v_mov_b32_e32 v92, 0
	v_mov_b32_e32 v93, 0
	v_mov_b32_e32 v94, 0
	v_mov_b32_e32 v95, 0
	v_mov_b32_e32 v96, 0
	v_mov_b32_e32 v97, 0
	v_mov_b32_e32 v98, 0
	v_mov_b32_e32 v99, 0
	v_mov_b32_e32 v100, 0
	v_mov_b32_e32 v101, 0
	v_mov_b32_e32 v102, 0
	v_mov_b32_e32 v103, 0
	v_mov_b32_e32 v104, 0
	v_mov_b32_e32 v105, 0
	v_mov_b32_e32 v106, 0
	v_mov_b32_e32 v107, 0
	v_mov_b32_e32 v108, 0
	v_mov_b32_e32 v109, 0
	v_mov_b32_e32 v110, 0
	v_mov_b32_e32 v111, 0
	v_mov_b32_e32 v112, 0
	v_mov_b32_e32 v113, 0
	v_mov_b32_e32 v114, 0
	v_mov_b32_e32 v115, 0
	v_mov_b32_e32 v116, 0
	v_mov_b32_e32 v117, 0
	v_mov_b32_e32 v118, 0
	v_mov_b32_e32 v119, 0
	v_mov_b32_e32 v120, 0
	v_mov_b32_e32 v121, 0
	v_mov_b32_e32 v122, 0
	v_mov_b32_e32 v123, 0
	v_mov_b32_e32 v124, 0
	v_mov_b32_e32 v125, 0
	v_mov_b32_e32 v126, 0
	v_mov_b32_e32 v127, 0
	s_mov_b32 s36, 0
	s_mov_b32 s37, 0x6000
	s_mov_b32 s1, 0
	s_waitcnt vmcnt(11)
	ds_write_b128 v177, v[128:131]
	s_waitcnt vmcnt(10)
	ds_write_b128 v177, v[132:135] offset:2048
	s_waitcnt vmcnt(9)
	ds_write_b128 v177, v[136:139] offset:4096
	s_waitcnt vmcnt(8)
	ds_write_b128 v177, v[140:143] offset:6144
	s_waitcnt vmcnt(7)
	ds_write_b128 v177, v[144:147] offset:8192
	s_waitcnt vmcnt(6)
	ds_write_b128 v177, v[148:151] offset:10240
	s_waitcnt vmcnt(5)
	ds_write_b128 v177, v[152:155] offset:12288
	s_waitcnt vmcnt(4)
	ds_write_b128 v177, v[156:159] offset:14336
	s_waitcnt vmcnt(3)
	ds_write_b128 v177, v[160:163] offset:16384
	s_waitcnt vmcnt(2)
	ds_write_b128 v177, v[164:167] offset:18432
	s_waitcnt vmcnt(1)
	ds_write_b128 v177, v[168:171] offset:20480
	s_waitcnt vmcnt(0)
	ds_write_b128 v177, v[172:175] offset:22528
	v_subrev_u32_e32 v196, 0x6000, v177
	v_add_u32_e32 v198, 0xc000, v177
	v_min_u32_e32 v177, v196, v198
	s_waitcnt lgkmcnt(0)
	s_barrier
.Lg5_loop:
	v_add_u32_e32 v190, s36, v186
	v_add_u32_e32 v191, s36, v187
	v_add_u32_e32 v250, s36, v188
	v_add_u32_e32 v251, s36, v189
	ds_read_b128 v[200:203], v190
	ds_read_b128 v[204:207], v190 offset:2048
	ds_read_b128 v[222:225], v250
	ds_read_b128 v[226:229], v250 offset:2048
	ds_read_b128 v[230:233], v250 offset:4096
	ds_read_b128 v[234:237], v250 offset:6144
	ds_read_b128 v[208:211], v191
	ds_read_b128 v[212:215], v191 offset:2048
	ds_read_b128 v[238:241], v251
	ds_read_b128 v[242:245], v251 offset:2048
	ds_read_b128 v[246:249], v251 offset:4096
	ds_read_b128 v[192:195], v251 offset:6144
	s_setprio 1
	s_waitcnt lgkmcnt(9)
	v_mfma_f32_32x32x16_bf16 v[112:127], v[200:203], v[222:225], v[112:127]
	global_load_dwordx4 v[128:131], v178, s[26:27]
	v_mfma_f32_32x32x16_bf16 v[48:63], v[204:207], v[222:225], v[48:63]
	global_load_dwordx4 v[132:135], v179, s[26:27]
	s_waitcnt lgkmcnt(8)
	v_mfma_f32_32x32x16_bf16 v[96:111], v[200:203], v[226:229], v[96:111]
	global_load_dwordx4 v[136:139], v180, s[26:27]
	v_mfma_f32_32x32x16_bf16 v[32:47], v[204:207], v[226:229], v[32:47]
	global_load_dwordx4 v[140:143], v181, s[26:27]
	s_waitcnt lgkmcnt(7)
	v_mfma_f32_32x32x16_bf16 v[80:95], v[200:203], v[230:233], v[80:95]
	global_load_dwordx4 v[144:147], v178, s[28:29]
	v_mfma_f32_32x32x16_bf16 v[16:31], v[204:207], v[230:233], v[16:31]
	global_load_dwordx4 v[148:151], v179, s[28:29]
	s_waitcnt lgkmcnt(6)
	v_mfma_f32_32x32x16_bf16 v[64:79], v[200:203], v[234:237], v[64:79]
	global_load_dwordx4 v[152:155], v180, s[28:29]
	v_mfma_f32_32x32x16_bf16 v[0:15], v[204:207], v[234:237], v[0:15]
	global_load_dwordx4 v[156:159], v181, s[28:29]
	s_waitcnt lgkmcnt(3)
	v_mfma_f32_32x32x16_bf16 v[112:127], v[208:211], v[238:241], v[112:127]
	global_load_dwordx4 v[160:163], v182, s[28:29]
	v_mfma_f32_32x32x16_bf16 v[48:63], v[212:215], v[238:241], v[48:63]
	global_load_dwordx4 v[164:167], v183, s[28:29]
	s_waitcnt lgkmcnt(2)
	v_mfma_f32_32x32x16_bf16 v[96:111], v[208:211], v[242:245], v[96:111]
	global_load_dwordx4 v[168:171], v184, s[28:29]
	v_mfma_f32_32x32x16_bf16 v[32:47], v[212:215], v[242:245], v[32:47]
	global_load_dwordx4 v[172:175], v185, s[28:29]
	s_waitcnt lgkmcnt(1)
	v_mfma_f32_32x32x16_bf16 v[80:95], v[208:211], v[246:249], v[80:95]
	v_mfma_f32_32x32x16_bf16 v[16:31], v[212:215], v[246:249], v[16:31]
	s_waitcnt lgkmcnt(0)
	v_mfma_f32_32x32x16_bf16 v[64:79], v[208:211], v[192:195], v[64:79]
	v_mfma_f32_32x32x16_bf16 v[0:15], v[212:215], v[192:195], v[0:15]
	s_setprio 0
	s_barrier
	v_xad_u32 v190, v186, 64, s37
	v_xad_u32 v191, v187, 64, s37
	v_xad_u32 v250, v188, 64, s37
	v_xad_u32 v251, v189, 64, s37
	ds_read_b128 v[200:203], v190
	ds_read_b128 v[204:207], v190 offset:2048
	ds_read_b128 v[222:225], v250
	ds_read_b128 v[226:229], v250 offset:2048
	ds_read_b128 v[230:233], v250 offset:4096
	ds_read_b128 v[234:237], v250 offset:6144
	ds_read_b128 v[208:211], v191
	ds_read_b128 v[212:215], v191 offset:2048
	ds_read_b128 v[238:241], v251
	ds_read_b128 v[242:245], v251 offset:2048
	ds_read_b128 v[246:249], v251 offset:4096
	ds_read_b128 v[192:195], v251 offset:6144
	s_setprio 1
	s_waitcnt lgkmcnt(9)
	v_mfma_f32_32x32x16_bf16 v[112:127], v[200:203], v[222:225], v[112:127]
	v_mfma_f32_32x32x16_bf16 v[48:63], v[204:207], v[222:225], v[48:63]
	s_waitcnt lgkmcnt(8)
	v_mfma_f32_32x32x16_bf16 v[96:111], v[200:203], v[226:229], v[96:111]
	s_waitcnt vmcnt(11)
	ds_write_b128 v177, v[128:131]
	v_mfma_f32_32x32x16_bf16 v[32:47], v[204:207], v[226:229], v[32:47]
	s_waitcnt vmcnt(10)
	ds_write_b128 v177, v[132:135] offset:2048
	s_waitcnt lgkmcnt(9)
	v_mfma_f32_32x32x16_bf16 v[80:95], v[200:203], v[230:233], v[80:95]
	s_waitcnt vmcnt(9)
	ds_write_b128 v177, v[136:139] offset:4096
	v_mfma_f32_32x32x16_bf16 v[16:31], v[204:207], v[230:233], v[16:31]
	s_waitcnt vmcnt(8)
	ds_write_b128 v177, v[140:143] offset:6144
	s_waitcnt lgkmcnt(10)
	v_mfma_f32_32x32x16_bf16 v[64:79], v[200:203], v[234:237], v[64:79]
	s_waitcnt vmcnt(7)
	ds_write_b128 v177, v[144:147] offset:8192
	v_mfma_f32_32x32x16_bf16 v[0:15], v[204:207], v[234:237], v[0:15]
	s_waitcnt vmcnt(6)
	ds_write_b128 v177, v[148:151] offset:10240
	s_waitcnt lgkmcnt(9)
	v_mfma_f32_32x32x16_bf16 v[112:127], v[208:211], v[238:241], v[112:127]
	s_waitcnt vmcnt(5)
	ds_write_b128 v177, v[152:155] offset:12288
	v_mfma_f32_32x32x16_bf16 v[48:63], v[212:215], v[238:241], v[48:63]
	s_waitcnt vmcnt(4)
	ds_write_b128 v177, v[156:159] offset:14336
	s_waitcnt lgkmcnt(10)
	v_mfma_f32_32x32x16_bf16 v[96:111], v[208:211], v[242:245], v[96:111]
	s_waitcnt vmcnt(3)
	ds_write_b128 v177, v[160:163] offset:16384
	v_mfma_f32_32x32x16_bf16 v[32:47], v[212:215], v[242:245], v[32:47]
	s_waitcnt vmcnt(2)
	ds_write_b128 v177, v[164:167] offset:18432
	s_waitcnt lgkmcnt(11)
	v_mfma_f32_32x32x16_bf16 v[80:95], v[208:211], v[246:249], v[80:95]
	s_waitcnt vmcnt(1)
	ds_write_b128 v177, v[168:171] offset:20480
	v_mfma_f32_32x32x16_bf16 v[16:31], v[212:215], v[246:249], v[16:31]
	s_waitcnt vmcnt(0)
	ds_write_b128 v177, v[172:175] offset:22528
	s_waitcnt lgkmcnt(12)
	v_mfma_f32_32x32x16_bf16 v[64:79], v[208:211], v[192:195], v[64:79]
	v_mfma_f32_32x32x16_bf16 v[0:15], v[212:215], v[192:195], v[0:15]
	s_setprio 0
	s_add_u32 s26, s26, 0x80
	s_addc_u32 s27, s27, 0
	s_add_u32 s28, s28, 0x80
	s_addc_u32 s29, s29, 0
	s_sub_i32 s36, s36, 0x6000
	s_cmp_lt_i32 s36, 0
	s_cselect_b32 s38, 0x12000, 0
	s_add_i32 s36, s36, s38
	s_sub_i32 s37, s37, 0x6000
	s_cmp_lt_i32 s37, 0
	s_cselect_b32 s38, 0x12000, 0
	s_add_i32 s37, s37, s38
	v_subrev_u32_e32 v196, 0x6000, v177
	v_add_u32_e32 v198, 0xc000, v177
	v_min_u32_e32 v177, v196, v198
	s_add_i32 s1, s1, 1
	s_cmp_lt_u32 s1, 15
	s_waitcnt lgkmcnt(0)
	s_barrier
	s_cbranch_scc1 .Lg5_loop
	v_add_u32_e32 v190, s36, v186
	v_add_u32_e32 v191, s36, v187
	v_add_u32_e32 v250, s36, v188
	v_add_u32_e32 v251, s36, v189
	ds_read_b128 v[200:203], v190
	ds_read_b128 v[204:207], v190 offset:2048
	ds_read_b128 v[222:225], v250
	ds_read_b128 v[226:229], v250 offset:2048
	ds_read_b128 v[230:233], v250 offset:4096
	ds_read_b128 v[234:237], v250 offset:6144
	ds_read_b128 v[208:211], v191
	ds_read_b128 v[212:215], v191 offset:2048
	ds_read_b128 v[238:241], v251
	ds_read_b128 v[242:245], v251 offset:2048
	ds_read_b128 v[246:249], v251 offset:4096
	ds_read_b128 v[192:195], v251 offset:6144
	s_setprio 1
	s_waitcnt lgkmcnt(9)
	v_mfma_f32_32x32x16_bf16 v[112:127], v[200:203], v[222:225], v[112:127]
	v_mfma_f32_32x32x16_bf16 v[48:63], v[204:207], v[222:225], v[48:63]
	s_waitcnt lgkmcnt(8)
	v_mfma_f32_32x32x16_bf16 v[96:111], v[200:203], v[226:229], v[96:111]
	v_mfma_f32_32x32x16_bf16 v[32:47], v[204:207], v[226:229], v[32:47]
	s_waitcnt lgkmcnt(7)
	v_mfma_f32_32x32x16_bf16 v[80:95], v[200:203], v[230:233], v[80:95]
	v_mfma_f32_32x32x16_bf16 v[16:31], v[204:207], v[230:233], v[16:31]
	s_waitcnt lgkmcnt(6)
	v_mfma_f32_32x32x16_bf16 v[64:79], v[200:203], v[234:237], v[64:79]
	v_mfma_f32_32x32x16_bf16 v[0:15], v[204:207], v[234:237], v[0:15]
	s_waitcnt lgkmcnt(3)
	v_mfma_f32_32x32x16_bf16 v[112:127], v[208:211], v[238:241], v[112:127]
	v_mfma_f32_32x32x16_bf16 v[48:63], v[212:215], v[238:241], v[48:63]
	s_waitcnt lgkmcnt(2)
	v_mfma_f32_32x32x16_bf16 v[96:111], v[208:211], v[242:245], v[96:111]
	v_mfma_f32_32x32x16_bf16 v[32:47], v[212:215], v[242:245], v[32:47]
	s_waitcnt lgkmcnt(1)
	v_mfma_f32_32x32x16_bf16 v[80:95], v[208:211], v[246:249], v[80:95]
	v_mfma_f32_32x32x16_bf16 v[16:31], v[212:215], v[246:249], v[16:31]
	s_waitcnt lgkmcnt(0)
	v_mfma_f32_32x32x16_bf16 v[64:79], v[208:211], v[192:195], v[64:79]
	v_mfma_f32_32x32x16_bf16 v[0:15], v[212:215], v[192:195], v[0:15]
	s_setprio 0
	v_xad_u32 v190, v186, 64, s37
	v_xad_u32 v191, v187, 64, s37
	v_xad_u32 v250, v188, 64, s37
	v_xad_u32 v251, v189, 64, s37
	ds_read_b128 v[200:203], v190
	ds_read_b128 v[204:207], v190 offset:2048
	ds_read_b128 v[222:225], v250
	ds_read_b128 v[226:229], v250 offset:2048
	ds_read_b128 v[230:233], v250 offset:4096
	ds_read_b128 v[234:237], v250 offset:6144
	ds_read_b128 v[208:211], v191
	ds_read_b128 v[212:215], v191 offset:2048
	ds_read_b128 v[238:241], v251
	ds_read_b128 v[242:245], v251 offset:2048
	ds_read_b128 v[246:249], v251 offset:4096
	ds_read_b128 v[192:195], v251 offset:6144
	s_setprio 1
	s_waitcnt lgkmcnt(9)
	v_mfma_f32_32x32x16_bf16 v[112:127], v[200:203], v[222:225], v[112:127]
	v_mfma_f32_32x32x16_bf16 v[48:63], v[204:207], v[222:225], v[48:63]
	s_waitcnt lgkmcnt(8)
	v_mfma_f32_32x32x16_bf16 v[96:111], v[200:203], v[226:229], v[96:111]
	v_mfma_f32_32x32x16_bf16 v[32:47], v[204:207], v[226:229], v[32:47]
	s_waitcnt lgkmcnt(7)
	v_mfma_f32_32x32x16_bf16 v[80:95], v[200:203], v[230:233], v[80:95]
	v_mfma_f32_32x32x16_bf16 v[16:31], v[204:207], v[230:233], v[16:31]
	s_waitcnt lgkmcnt(6)
	v_mfma_f32_32x32x16_bf16 v[64:79], v[200:203], v[234:237], v[64:79]
	v_mfma_f32_32x32x16_bf16 v[0:15], v[204:207], v[234:237], v[0:15]
	s_waitcnt lgkmcnt(3)
	v_mfma_f32_32x32x16_bf16 v[112:127], v[208:211], v[238:241], v[112:127]
	v_mfma_f32_32x32x16_bf16 v[48:63], v[212:215], v[238:241], v[48:63]
	s_waitcnt lgkmcnt(2)
	v_mfma_f32_32x32x16_bf16 v[96:111], v[208:211], v[242:245], v[96:111]
	v_mfma_f32_32x32x16_bf16 v[32:47], v[212:215], v[242:245], v[32:47]
	s_waitcnt lgkmcnt(1)
	v_mfma_f32_32x32x16_bf16 v[80:95], v[208:211], v[246:249], v[80:95]
	v_mfma_f32_32x32x16_bf16 v[16:31], v[212:215], v[246:249], v[16:31]
	s_waitcnt lgkmcnt(0)
	v_mfma_f32_32x32x16_bf16 v[64:79], v[208:211], v[192:195], v[64:79]
	v_mfma_f32_32x32x16_bf16 v[0:15], v[212:215], v[192:195], v[0:15]
	s_setprio 0
	s_nop 7
	s_nop 7
	s_branch .LBB0_482

.LBB0_551:
	s_lshl_b32 s6, s5, 5
	s_and_b32 s26, s6, 0xffffff80
	s_lshl_b32 s6, s5, 8
	s_ashr_i32 s27, s26, 31
	s_and_b32 s68, s6, 0x300
	s_lshl_b64 s[8:9], s[26:27], 13
	s_add_u32 s28, s70, s8
	s_addc_u32 s29, s71, s9
	s_lshl_b32 s7, s68, 13
	s_add_u32 s38, s80, s7
	s_addc_u32 s39, s81, 0
	v_lshrrev_b32_e32 v196, 3, v197
	v_and_b32_e32 v198, 7, v197
	v_lshlrev_b32_e32 v176, 13, v196
	v_lshl_or_b32 v176, v198, 4, v176
	v_add_u32_e32 v177, 0x40000, v176
	v_add_u32_e32 v178, 0x80000, v176
	v_add_u32_e32 v179, 0xc0000, v176
	v_add_u32_e32 v180, 0x100000, v176
	v_add_u32_e32 v181, 0x140000, v176
	v_add_u32_e32 v182, 0x180000, v176
	v_add_u32_e32 v184, 0x1c0000, v176
	global_load_dwordx4 v[128:131], v176, s[28:29]
	global_load_dwordx4 v[132:135], v177, s[28:29]
	global_load_dwordx4 v[136:139], v178, s[28:29]
	global_load_dwordx4 v[140:143], v179, s[28:29]
	global_load_dwordx4 v[144:147], v176, s[38:39]
	global_load_dwordx4 v[148:151], v177, s[38:39]
	global_load_dwordx4 v[152:155], v178, s[38:39]
	global_load_dwordx4 v[156:159], v179, s[38:39]
	global_load_dwordx4 v[160:163], v180, s[38:39]
	global_load_dwordx4 v[164:167], v181, s[38:39]
	global_load_dwordx4 v[168:171], v182, s[38:39]
	global_load_dwordx4 v[172:175], v184, s[38:39]
	s_add_u32 s28, s28, 0x80
	s_addc_u32 s29, s29, 0
	s_add_u32 s38, s38, 0x80
	s_addc_u32 s39, s39, 0
	v_bfe_u32 v217, v197, 5, 2
	v_and_b32_e32 v218, 3, v198
	v_xor_b32_e32 v218, v218, v217
	v_lshlrev_b32_e32 v218, 4, v218
	v_lshl_or_b32 v185, v196, 6, v218
	v_lshrrev_b32_e32 v217, 2, v198
	v_lshlrev_b32_e32 v218, 6, v217
	v_xor_b32_e32 v185, v185, v218
	v_mul_u32_u24_e32 v217, 0x6000, v217
	v_add_u32_e32 v185, v185, v217
	v_and_b32_e32 v196, 31, v197
	v_bfe_u32 v198, v197, 5, 1
	v_bfe_u32 v217, v197, 2, 2
	v_xor_b32_e32 v218, v198, v217
	v_xor_b32_e32 v221, 2, v218
	v_lshrrev_b32_e32 v198, 7, v197
	v_lshl_or_b32 v198, v198, 6, v196
	v_lshlrev_b32_e32 v198, 6, v198
	v_lshl_or_b32 v186, v218, 4, v198
	v_lshl_or_b32 v187, v221, 4, v198
	v_bfe_u32 v198, v197, 6, 1
	v_mul_u32_u24_e32 v198, 128, v198
	v_add_u32_e32 v198, v198, v196
	v_lshlrev_b32_e32 v198, 6, v198
	v_add_u32_e32 v198, 0x2000, v198
	v_lshl_or_b32 v188, v218, 4, v198
	v_lshl_or_b32 v189, v221, 4, v198
	v_mov_b32_e32 v0, 0
	v_mov_b32_e32 v1, 0
	v_mov_b32_e32 v2, 0
	v_mov_b32_e32 v3, 0
	v_mov_b32_e32 v4, 0
	v_mov_b32_e32 v5, 0
	v_mov_b32_e32 v6, 0
	v_mov_b32_e32 v7, 0
	v_mov_b32_e32 v8, 0
	v_mov_b32_e32 v9, 0
	v_mov_b32_e32 v10, 0
	v_mov_b32_e32 v11, 0
	v_mov_b32_e32 v12, 0
	v_mov_b32_e32 v13, 0
	v_mov_b32_e32 v14, 0
	v_mov_b32_e32 v15, 0
	v_mov_b32_e32 v16, 0
	v_mov_b32_e32 v17, 0
	v_mov_b32_e32 v18, 0
	v_mov_b32_e32 v19, 0
	v_mov_b32_e32 v20, 0
	v_mov_b32_e32 v21, 0
	v_mov_b32_e32 v22, 0
	v_mov_b32_e32 v23, 0
	v_mov_b32_e32 v24, 0
	v_mov_b32_e32 v25, 0
	v_mov_b32_e32 v26, 0
	v_mov_b32_e32 v27, 0
	v_mov_b32_e32 v28, 0
	v_mov_b32_e32 v29, 0
	v_mov_b32_e32 v30, 0
	v_mov_b32_e32 v31, 0
	v_mov_b32_e32 v32, 0
	v_mov_b32_e32 v33, 0
	v_mov_b32_e32 v34, 0
	v_mov_b32_e32 v35, 0
	v_mov_b32_e32 v36, 0
	v_mov_b32_e32 v37, 0
	v_mov_b32_e32 v38, 0
	v_mov_b32_e32 v39, 0
	v_mov_b32_e32 v40, 0
	v_mov_b32_e32 v41, 0
	v_mov_b32_e32 v42, 0
	v_mov_b32_e32 v43, 0
	v_mov_b32_e32 v44, 0
	v_mov_b32_e32 v45, 0
	v_mov_b32_e32 v46, 0
	v_mov_b32_e32 v47, 0
	v_mov_b32_e32 v48, 0
	v_mov_b32_e32 v49, 0
	v_mov_b32_e32 v50, 0
	v_mov_b32_e32 v51, 0
	v_mov_b32_e32 v52, 0
	v_mov_b32_e32 v53, 0
	v_mov_b32_e32 v54, 0
	v_mov_b32_e32 v55, 0
	v_mov_b32_e32 v56, 0
	v_mov_b32_e32 v57, 0
	v_mov_b32_e32 v58, 0
	v_mov_b32_e32 v59, 0
	v_mov_b32_e32 v60, 0
	v_mov_b32_e32 v61, 0
	v_mov_b32_e32 v62, 0
	v_mov_b32_e32 v63, 0
	v_mov_b32_e32 v64, 0
	v_mov_b32_e32 v65, 0
	v_mov_b32_e32 v66, 0
	v_mov_b32_e32 v67, 0
	v_mov_b32_e32 v68, 0
	v_mov_b32_e32 v69, 0
	v_mov_b32_e32 v70, 0
	v_mov_b32_e32 v71, 0
	v_mov_b32_e32 v72, 0
	v_mov_b32_e32 v73, 0
	v_mov_b32_e32 v74, 0
	v_mov_b32_e32 v75, 0
	v_mov_b32_e32 v76, 0
	v_mov_b32_e32 v77, 0
	v_mov_b32_e32 v78, 0
	v_mov_b32_e32 v79, 0
	v_mov_b32_e32 v80, 0
	v_mov_b32_e32 v81, 0
	v_mov_b32_e32 v82, 0
	v_mov_b32_e32 v83, 0
	v_mov_b32_e32 v84, 0
	v_mov_b32_e32 v85, 0
	v_mov_b32_e32 v86, 0
	v_mov_b32_e32 v87, 0
	v_mov_b32_e32 v88, 0
	v_mov_b32_e32 v89, 0
	v_mov_b32_e32 v90, 0
	v_mov_b32_e32 v91, 0
	v_mov_b32_e32 v92, 0
	v_mov_b32_e32 v93, 0
	v_mov_b32_e32 v94, 0
	v_mov_b32_e32 v95, 0
	v_mov_b32_e32 v96, 0
	v_mov_b32_e32 v97, 0
	v_mov_b32_e32 v98, 0
	v_mov_b32_e32 v99, 0
	v_mov_b32_e32 v100, 0
	v_mov_b32_e32 v101, 0
	v_mov_b32_e32 v102, 0
	v_mov_b32_e32 v103, 0
	v_mov_b32_e32 v104, 0
	v_mov_b32_e32 v105, 0
	v_mov_b32_e32 v106, 0
	v_mov_b32_e32 v107, 0
	v_mov_b32_e32 v108, 0
	v_mov_b32_e32 v109, 0
	v_mov_b32_e32 v110, 0
	v_mov_b32_e32 v111, 0
	v_mov_b32_e32 v112, 0
	v_mov_b32_e32 v113, 0
	v_mov_b32_e32 v114, 0
	v_mov_b32_e32 v115, 0
	v_mov_b32_e32 v116, 0
	v_mov_b32_e32 v117, 0
	v_mov_b32_e32 v118, 0
	v_mov_b32_e32 v119, 0
	v_mov_b32_e32 v120, 0
	v_mov_b32_e32 v121, 0
	v_mov_b32_e32 v122, 0
	v_mov_b32_e32 v123, 0
	v_mov_b32_e32 v124, 0
	v_mov_b32_e32 v125, 0
	v_mov_b32_e32 v126, 0
	v_mov_b32_e32 v127, 0
	s_mov_b32 s40, 0
	s_mov_b32 s41, 0x6000
	s_mov_b32 s7, 0
	s_waitcnt vmcnt(11)
	ds_write_b128 v185, v[128:131]
	s_waitcnt vmcnt(10)
	ds_write_b128 v185, v[132:135] offset:2048
	s_waitcnt vmcnt(9)
	ds_write_b128 v185, v[136:139] offset:4096
	s_waitcnt vmcnt(8)
	ds_write_b128 v185, v[140:143] offset:6144
	s_waitcnt vmcnt(7)
	ds_write_b128 v185, v[144:147] offset:8192
	s_waitcnt vmcnt(6)
	ds_write_b128 v185, v[148:151] offset:10240
	s_waitcnt vmcnt(5)
	ds_write_b128 v185, v[152:155] offset:12288
	s_waitcnt vmcnt(4)
	ds_write_b128 v185, v[156:159] offset:14336
	s_waitcnt vmcnt(3)
	ds_write_b128 v185, v[160:163] offset:16384
	s_waitcnt vmcnt(2)
	ds_write_b128 v185, v[164:167] offset:18432
	s_waitcnt vmcnt(1)
	ds_write_b128 v185, v[168:171] offset:20480
	s_waitcnt vmcnt(0)
	ds_write_b128 v185, v[172:175] offset:22528
	v_subrev_u32_e32 v196, 0x6000, v185
	v_add_u32_e32 v198, 0xc000, v185
	v_min_u32_e32 v185, v196, v198
	s_waitcnt lgkmcnt(0)
	s_barrier
.Lg6_loop:
	v_add_u32_e32 v190, s40, v186
	v_add_u32_e32 v191, s40, v187
	v_add_u32_e32 v250, s40, v188
	v_add_u32_e32 v251, s40, v189
	ds_read_b128 v[200:203], v190
	ds_read_b128 v[204:207], v190 offset:2048
	ds_read_b128 v[222:225], v250
	ds_read_b128 v[226:229], v250 offset:2048
	ds_read_b128 v[230:233], v250 offset:4096
	ds_read_b128 v[234:237], v250 offset:6144
	ds_read_b128 v[208:211], v191
	ds_read_b128 v[212:215], v191 offset:2048
	ds_read_b128 v[238:241], v251
	ds_read_b128 v[242:245], v251 offset:2048
	ds_read_b128 v[246:249], v251 offset:4096
	ds_read_b128 v[192:195], v251 offset:6144
	s_setprio 1
	s_waitcnt lgkmcnt(9)
	v_mfma_f32_32x32x16_bf16 v[112:127], v[200:203], v[222:225], v[112:127]
	global_load_dwordx4 v[128:131], v176, s[28:29]
	v_mfma_f32_32x32x16_bf16 v[48:63], v[204:207], v[222:225], v[48:63]
	global_load_dwordx4 v[132:135], v177, s[28:29]
	s_waitcnt lgkmcnt(8)
	v_mfma_f32_32x32x16_bf16 v[96:111], v[200:203], v[226:229], v[96:111]
	global_load_dwordx4 v[136:139], v178, s[28:29]
	v_mfma_f32_32x32x16_bf16 v[32:47], v[204:207], v[226:229], v[32:47]
	global_load_dwordx4 v[140:143], v179, s[28:29]
	s_waitcnt lgkmcnt(7)
	v_mfma_f32_32x32x16_bf16 v[80:95], v[200:203], v[230:233], v[80:95]
	global_load_dwordx4 v[144:147], v176, s[38:39]
	v_mfma_f32_32x32x16_bf16 v[16:31], v[204:207], v[230:233], v[16:31]
	global_load_dwordx4 v[148:151], v177, s[38:39]
	s_waitcnt lgkmcnt(6)
	v_mfma_f32_32x32x16_bf16 v[64:79], v[200:203], v[234:237], v[64:79]
	global_load_dwordx4 v[152:155], v178, s[38:39]
	v_mfma_f32_32x32x16_bf16 v[0:15], v[204:207], v[234:237], v[0:15]
	global_load_dwordx4 v[156:159], v179, s[38:39]
	s_waitcnt lgkmcnt(3)
	v_mfma_f32_32x32x16_bf16 v[112:127], v[208:211], v[238:241], v[112:127]
	global_load_dwordx4 v[160:163], v180, s[38:39]
	v_mfma_f32_32x32x16_bf16 v[48:63], v[212:215], v[238:241], v[48:63]
	global_load_dwordx4 v[164:167], v181, s[38:39]
	s_waitcnt lgkmcnt(2)
	v_mfma_f32_32x32x16_bf16 v[96:111], v[208:211], v[242:245], v[96:111]
	global_load_dwordx4 v[168:171], v182, s[38:39]
	v_mfma_f32_32x32x16_bf16 v[32:47], v[212:215], v[242:245], v[32:47]
	global_load_dwordx4 v[172:175], v184, s[38:39]
	s_waitcnt lgkmcnt(1)
	v_mfma_f32_32x32x16_bf16 v[80:95], v[208:211], v[246:249], v[80:95]
	v_mfma_f32_32x32x16_bf16 v[16:31], v[212:215], v[246:249], v[16:31]
	s_waitcnt lgkmcnt(0)
	v_mfma_f32_32x32x16_bf16 v[64:79], v[208:211], v[192:195], v[64:79]
	v_mfma_f32_32x32x16_bf16 v[0:15], v[212:215], v[192:195], v[0:15]
	s_setprio 0
	s_barrier
	v_xad_u32 v190, v186, 64, s41
	v_xad_u32 v191, v187, 64, s41
	v_xad_u32 v250, v188, 64, s41
	v_xad_u32 v251, v189, 64, s41
	ds_read_b128 v[200:203], v190
	ds_read_b128 v[204:207], v190 offset:2048
	ds_read_b128 v[222:225], v250
	ds_read_b128 v[226:229], v250 offset:2048
	ds_read_b128 v[230:233], v250 offset:4096
	ds_read_b128 v[234:237], v250 offset:6144
	ds_read_b128 v[208:211], v191
	ds_read_b128 v[212:215], v191 offset:2048
	ds_read_b128 v[238:241], v251
	ds_read_b128 v[242:245], v251 offset:2048
	ds_read_b128 v[246:249], v251 offset:4096
	ds_read_b128 v[192:195], v251 offset:6144
	s_setprio 1
	s_waitcnt lgkmcnt(9)
	v_mfma_f32_32x32x16_bf16 v[112:127], v[200:203], v[222:225], v[112:127]
	v_mfma_f32_32x32x16_bf16 v[48:63], v[204:207], v[222:225], v[48:63]
	s_waitcnt lgkmcnt(8)
	v_mfma_f32_32x32x16_bf16 v[96:111], v[200:203], v[226:229], v[96:111]
	s_waitcnt vmcnt(11)
	ds_write_b128 v185, v[128:131]
	v_mfma_f32_32x32x16_bf16 v[32:47], v[204:207], v[226:229], v[32:47]
	s_waitcnt vmcnt(10)
	ds_write_b128 v185, v[132:135] offset:2048
	s_waitcnt lgkmcnt(9)
	v_mfma_f32_32x32x16_bf16 v[80:95], v[200:203], v[230:233], v[80:95]
	s_waitcnt vmcnt(9)
	ds_write_b128 v185, v[136:139] offset:4096
	v_mfma_f32_32x32x16_bf16 v[16:31], v[204:207], v[230:233], v[16:31]
	s_waitcnt vmcnt(8)
	ds_write_b128 v185, v[140:143] offset:6144
	s_waitcnt lgkmcnt(10)
	v_mfma_f32_32x32x16_bf16 v[64:79], v[200:203], v[234:237], v[64:79]
	s_waitcnt vmcnt(7)
	ds_write_b128 v185, v[144:147] offset:8192
	v_mfma_f32_32x32x16_bf16 v[0:15], v[204:207], v[234:237], v[0:15]
	s_waitcnt vmcnt(6)
	ds_write_b128 v185, v[148:151] offset:10240
	s_waitcnt lgkmcnt(9)
	v_mfma_f32_32x32x16_bf16 v[112:127], v[208:211], v[238:241], v[112:127]
	s_waitcnt vmcnt(5)
	ds_write_b128 v185, v[152:155] offset:12288
	v_mfma_f32_32x32x16_bf16 v[48:63], v[212:215], v[238:241], v[48:63]
	s_waitcnt vmcnt(4)
	ds_write_b128 v185, v[156:159] offset:14336
	s_waitcnt lgkmcnt(10)
	v_mfma_f32_32x32x16_bf16 v[96:111], v[208:211], v[242:245], v[96:111]
	s_waitcnt vmcnt(3)
	ds_write_b128 v185, v[160:163] offset:16384
	v_mfma_f32_32x32x16_bf16 v[32:47], v[212:215], v[242:245], v[32:47]
	s_waitcnt vmcnt(2)
	ds_write_b128 v185, v[164:167] offset:18432
	s_waitcnt lgkmcnt(11)
	v_mfma_f32_32x32x16_bf16 v[80:95], v[208:211], v[246:249], v[80:95]
	s_waitcnt vmcnt(1)
	ds_write_b128 v185, v[168:171] offset:20480
	v_mfma_f32_32x32x16_bf16 v[16:31], v[212:215], v[246:249], v[16:31]
	s_waitcnt vmcnt(0)
	ds_write_b128 v185, v[172:175] offset:22528
	s_waitcnt lgkmcnt(12)
	v_mfma_f32_32x32x16_bf16 v[64:79], v[208:211], v[192:195], v[64:79]
	v_mfma_f32_32x32x16_bf16 v[0:15], v[212:215], v[192:195], v[0:15]
	s_setprio 0
	s_add_u32 s28, s28, 0x80
	s_addc_u32 s29, s29, 0
	s_add_u32 s38, s38, 0x80
	s_addc_u32 s39, s39, 0
	s_sub_i32 s40, s40, 0x6000
	s_cmp_lt_i32 s40, 0
	s_cselect_b32 s42, 0x12000, 0
	s_add_i32 s40, s40, s42
	s_sub_i32 s41, s41, 0x6000
	s_cmp_lt_i32 s41, 0
	s_cselect_b32 s42, 0x12000, 0
	s_add_i32 s41, s41, s42
	v_subrev_u32_e32 v196, 0x6000, v185
	v_add_u32_e32 v198, 0xc000, v185
	v_min_u32_e32 v185, v196, v198
	s_add_i32 s7, s7, 1
	s_cmp_lt_u32 s7, 63
	s_waitcnt lgkmcnt(0)
	s_barrier
	s_cbranch_scc1 .Lg6_loop
	v_add_u32_e32 v190, s40, v186
	v_add_u32_e32 v191, s40, v187
	v_add_u32_e32 v250, s40, v188
	v_add_u32_e32 v251, s40, v189
	ds_read_b128 v[200:203], v190
	ds_read_b128 v[204:207], v190 offset:2048
	ds_read_b128 v[222:225], v250
	ds_read_b128 v[226:229], v250 offset:2048
	ds_read_b128 v[230:233], v250 offset:4096
	ds_read_b128 v[234:237], v250 offset:6144
	ds_read_b128 v[208:211], v191
	ds_read_b128 v[212:215], v191 offset:2048
	ds_read_b128 v[238:241], v251
	ds_read_b128 v[242:245], v251 offset:2048
	ds_read_b128 v[246:249], v251 offset:4096
	ds_read_b128 v[192:195], v251 offset:6144
	s_setprio 1
	s_waitcnt lgkmcnt(9)
	v_mfma_f32_32x32x16_bf16 v[112:127], v[200:203], v[222:225], v[112:127]
	v_mfma_f32_32x32x16_bf16 v[48:63], v[204:207], v[222:225], v[48:63]
	s_waitcnt lgkmcnt(8)
	v_mfma_f32_32x32x16_bf16 v[96:111], v[200:203], v[226:229], v[96:111]
	v_mfma_f32_32x32x16_bf16 v[32:47], v[204:207], v[226:229], v[32:47]
	s_waitcnt lgkmcnt(7)
	v_mfma_f32_32x32x16_bf16 v[80:95], v[200:203], v[230:233], v[80:95]
	v_mfma_f32_32x32x16_bf16 v[16:31], v[204:207], v[230:233], v[16:31]
	s_waitcnt lgkmcnt(6)
	v_mfma_f32_32x32x16_bf16 v[64:79], v[200:203], v[234:237], v[64:79]
	v_mfma_f32_32x32x16_bf16 v[0:15], v[204:207], v[234:237], v[0:15]
	s_waitcnt lgkmcnt(3)
	v_mfma_f32_32x32x16_bf16 v[112:127], v[208:211], v[238:241], v[112:127]
	v_mfma_f32_32x32x16_bf16 v[48:63], v[212:215], v[238:241], v[48:63]
	s_waitcnt lgkmcnt(2)
	v_mfma_f32_32x32x16_bf16 v[96:111], v[208:211], v[242:245], v[96:111]
	v_mfma_f32_32x32x16_bf16 v[32:47], v[212:215], v[242:245], v[32:47]
	s_waitcnt lgkmcnt(1)
	v_mfma_f32_32x32x16_bf16 v[80:95], v[208:211], v[246:249], v[80:95]
	v_mfma_f32_32x32x16_bf16 v[16:31], v[212:215], v[246:249], v[16:31]
	s_waitcnt lgkmcnt(0)
	v_mfma_f32_32x32x16_bf16 v[64:79], v[208:211], v[192:195], v[64:79]
	v_mfma_f32_32x32x16_bf16 v[0:15], v[212:215], v[192:195], v[0:15]
	s_setprio 0
	v_xad_u32 v190, v186, 64, s41
	v_xad_u32 v191, v187, 64, s41
	v_xad_u32 v250, v188, 64, s41
	v_xad_u32 v251, v189, 64, s41
	ds_read_b128 v[200:203], v190
	ds_read_b128 v[204:207], v190 offset:2048
	ds_read_b128 v[222:225], v250
	ds_read_b128 v[226:229], v250 offset:2048
	ds_read_b128 v[230:233], v250 offset:4096
	ds_read_b128 v[234:237], v250 offset:6144
	ds_read_b128 v[208:211], v191
	ds_read_b128 v[212:215], v191 offset:2048
	ds_read_b128 v[238:241], v251
	ds_read_b128 v[242:245], v251 offset:2048
	ds_read_b128 v[246:249], v251 offset:4096
	ds_read_b128 v[192:195], v251 offset:6144
	s_setprio 1
	s_waitcnt lgkmcnt(9)
	v_mfma_f32_32x32x16_bf16 v[112:127], v[200:203], v[222:225], v[112:127]
	v_mfma_f32_32x32x16_bf16 v[48:63], v[204:207], v[222:225], v[48:63]
	s_waitcnt lgkmcnt(8)
	v_mfma_f32_32x32x16_bf16 v[96:111], v[200:203], v[226:229], v[96:111]
	v_mfma_f32_32x32x16_bf16 v[32:47], v[204:207], v[226:229], v[32:47]
	s_waitcnt lgkmcnt(7)
	v_mfma_f32_32x32x16_bf16 v[80:95], v[200:203], v[230:233], v[80:95]
	v_mfma_f32_32x32x16_bf16 v[16:31], v[204:207], v[230:233], v[16:31]
	s_waitcnt lgkmcnt(6)
	v_mfma_f32_32x32x16_bf16 v[64:79], v[200:203], v[234:237], v[64:79]
	v_mfma_f32_32x32x16_bf16 v[0:15], v[204:207], v[234:237], v[0:15]
	s_waitcnt lgkmcnt(3)
	v_mfma_f32_32x32x16_bf16 v[112:127], v[208:211], v[238:241], v[112:127]
	v_mfma_f32_32x32x16_bf16 v[48:63], v[212:215], v[238:241], v[48:63]
	s_waitcnt lgkmcnt(2)
	v_mfma_f32_32x32x16_bf16 v[96:111], v[208:211], v[242:245], v[96:111]
	v_mfma_f32_32x32x16_bf16 v[32:47], v[212:215], v[242:245], v[32:47]
	s_waitcnt lgkmcnt(1)
	v_mfma_f32_32x32x16_bf16 v[80:95], v[208:211], v[246:249], v[80:95]
	v_mfma_f32_32x32x16_bf16 v[16:31], v[212:215], v[246:249], v[16:31]
	s_waitcnt lgkmcnt(0)
	v_mfma_f32_32x32x16_bf16 v[64:79], v[208:211], v[192:195], v[64:79]
	v_mfma_f32_32x32x16_bf16 v[0:15], v[212:215], v[192:195], v[0:15]
	s_setprio 0
	s_nop 7
	s_nop 7
